# ffn_out outputs and ffn_in-phase weight transposes stored write-through; XCD leaders skip the L2 writeback at the three barriers after ffn_out
# baseline (speedup 1.0000x reference)
.LBB0_750:
	v_or_b32_e32 v114, v115, v114
	v_lshl_add_u32 v24, v114, 3, 0
	v_add_u32_e32 v24, 0x24000, v24
	ds_read_b64 v[100:101], v24
	v_add_u32_e32 v98, s63, v114
	s_mov_b64 s[50:51], -1
	s_and_b64 vcc, exec, s[0:1]
	v_ashrrev_i32_e32 v99, 31, v98
	s_waitcnt lgkmcnt(0)
	v_sub_f32_e32 v25, v81, v100
	v_sub_f32_e32 v24, v80, v100
	v_sub_f32_e32 v27, v79, v100
	v_sub_f32_e32 v26, v78, v100
	v_pk_mul_f32 v[28:29], v[26:27], v[100:101] op_sel:[0,1]
	v_pk_mul_f32 v[24:25], v[24:25], v[100:101] op_sel:[0,1]
	v_sub_f32_e32 v31, v75, v100
	s_waitcnt vmcnt(0)
	v_pk_fma_f32 v[26:27], v[18:19], v[24:25], v[22:23]
	v_pk_fma_f32 v[24:25], v[16:17], v[28:29], v[20:21]
	v_sub_f32_e32 v29, v77, v100
	v_sub_f32_e32 v28, v76, v100
	v_sub_f32_e32 v30, v74, v100
	v_pk_mul_f32 v[74:75], v[100:101], v[30:31] op_sel:[1,0]
	v_pk_mul_f32 v[28:29], v[100:101], v[28:29] op_sel:[1,0]
	s_nop 0
	v_pk_fma_f32 v[30:31], v[2:3], v[28:29], v[6:7]
	v_pk_fma_f32 v[28:29], v[0:1], v[74:75], v[4:5]
	v_lshlrev_b64 v[74:75], 1, v[72:73]
	s_cbranch_vccz .LBB0_752
	v_pk_fma_f32 v[80:81], v[112:113], v[26:27], v[14:15]
	v_pk_fma_f32 v[116:117], v[106:107], v[24:25], v[12:13]
	v_pk_fma_f32 v[118:119], v[108:109], v[28:29], v[8:9]
	v_cvt_pk_bf16_f32 v116, v116, v117
	v_cvt_pk_bf16_f32 v117, v80, v81
	v_pk_fma_f32 v[80:81], v[110:111], v[30:31], v[10:11]
	v_cvt_pk_bf16_f32 v118, v118, v119
	v_cvt_pk_bf16_f32 v119, v80, v81
	v_lshlrev_b64 v[80:81], 11, v[98:99]
	v_lshl_add_u64 v[120:121], s[30:31], 0, v[80:81]
	v_cvt_pk_bf16_f32 v76, v24, v25
	v_cvt_pk_bf16_f32 v77, v26, v27
	v_cvt_pk_bf16_f32 v78, v28, v29
	v_cvt_pk_bf16_f32 v79, v30, v31
	v_lshl_add_u64 v[120:121], v[120:121], 0, v[74:75]
	global_store_dwordx4 v[120:121], v[76:79], off sc1
	s_mov_b64 s[50:51], 0
	s_nop 0
	v_lshl_add_u64 v[76:77], s[42:43], 0, v[80:81]
	v_lshl_add_u64 v[76:77], v[76:77], 0, v[74:75]
	global_store_dwordx4 v[76:77], v[116:119], off sc1

.LBB0_754:
	s_nop 0
	v_or_b32_e32 v24, 16, v114
	v_lshl_add_u32 v25, v24, 3, 0
	v_add_u32_e32 v25, 0x24000, v25
	ds_read_b64 v[78:79], v25
	v_add_u32_e32 v76, s63, v24
	s_mov_b64 s[50:51], -1
	s_and_b64 vcc, exec, s[40:41]
	v_ashrrev_i32_e32 v77, 31, v76
	s_waitcnt lgkmcnt(0)
	v_sub_f32_e32 v25, v63, v78
	v_sub_f32_e32 v24, v62, v78
	v_sub_f32_e32 v27, v61, v78
	v_sub_f32_e32 v26, v60, v78
	v_pk_mul_f32 v[28:29], v[26:27], v[78:79] op_sel:[0,1]
	v_pk_mul_f32 v[24:25], v[24:25], v[78:79] op_sel:[0,1]
	v_sub_f32_e32 v31, v57, v78
	v_pk_fma_f32 v[26:27], v[18:19], v[24:25], v[22:23]
	v_pk_fma_f32 v[24:25], v[16:17], v[28:29], v[20:21]
	v_sub_f32_e32 v29, v59, v78
	v_sub_f32_e32 v28, v58, v78
	v_sub_f32_e32 v30, v56, v78
	v_pk_mul_f32 v[56:57], v[78:79], v[30:31] op_sel:[1,0]
	v_pk_mul_f32 v[28:29], v[78:79], v[28:29] op_sel:[1,0]
	s_nop 0
	v_pk_fma_f32 v[30:31], v[2:3], v[28:29], v[6:7]
	v_pk_fma_f32 v[28:29], v[0:1], v[56:57], v[4:5]
	s_cbranch_vccnz .LBB0_756
	v_pk_fma_f32 v[62:63], v[112:113], v[26:27], v[14:15]
	v_pk_fma_f32 v[60:61], v[106:107], v[24:25], v[12:13]
	v_pk_fma_f32 v[80:81], v[110:111], v[30:31], v[10:11]
	v_cvt_pk_bf16_f32 v60, v60, v61
	v_cvt_pk_bf16_f32 v61, v62, v63
	v_pk_fma_f32 v[62:63], v[108:109], v[28:29], v[8:9]
	v_cvt_pk_bf16_f32 v56, v24, v25
	v_cvt_pk_bf16_f32 v62, v62, v63
	v_cvt_pk_bf16_f32 v63, v80, v81
	v_lshlrev_b64 v[80:81], 11, v[76:77]
	v_lshl_add_u64 v[116:117], s[30:31], 0, v[80:81]
	v_cvt_pk_bf16_f32 v57, v26, v27
	v_cvt_pk_bf16_f32 v58, v28, v29
	v_cvt_pk_bf16_f32 v59, v30, v31
	v_lshl_add_u64 v[116:117], v[116:117], 0, v[74:75]
	global_store_dwordx4 v[116:117], v[56:59], off sc1
	s_mov_b64 s[50:51], 0
	s_nop 0
	v_lshl_add_u64 v[56:57], s[42:43], 0, v[80:81]
	v_lshl_add_u64 v[56:57], v[56:57], 0, v[74:75]
	global_store_dwordx4 v[56:57], v[60:63], off sc1

.LBB0_758:
	s_nop 0
	v_or_b32_e32 v24, 32, v114
	v_lshl_add_u32 v25, v24, 3, 0
	v_add_u32_e32 v25, 0x24000, v25
	ds_read_b64 v[58:59], v25
	v_add_u32_e32 v56, s63, v24
	s_mov_b64 s[50:51], -1
	s_and_b64 vcc, exec, s[40:41]
	v_ashrrev_i32_e32 v57, 31, v56
	s_waitcnt lgkmcnt(0)
	v_sub_f32_e32 v25, v47, v58
	v_sub_f32_e32 v24, v46, v58
	v_sub_f32_e32 v27, v45, v58
	v_sub_f32_e32 v26, v44, v58
	v_pk_mul_f32 v[28:29], v[26:27], v[58:59] op_sel:[0,1]
	v_pk_mul_f32 v[24:25], v[24:25], v[58:59] op_sel:[0,1]
	v_sub_f32_e32 v31, v41, v58
	v_pk_fma_f32 v[26:27], v[18:19], v[24:25], v[22:23]
	v_pk_fma_f32 v[24:25], v[16:17], v[28:29], v[20:21]
	v_sub_f32_e32 v29, v43, v58
	v_sub_f32_e32 v28, v42, v58
	v_sub_f32_e32 v30, v40, v58
	v_pk_mul_f32 v[40:41], v[58:59], v[30:31] op_sel:[1,0]
	v_pk_mul_f32 v[28:29], v[58:59], v[28:29] op_sel:[1,0]
	s_nop 0
	v_pk_fma_f32 v[30:31], v[2:3], v[28:29], v[6:7]
	v_pk_fma_f32 v[28:29], v[0:1], v[40:41], v[4:5]
	s_cbranch_vccnz .LBB0_760
	v_pk_fma_f32 v[46:47], v[112:113], v[26:27], v[14:15]
	v_pk_fma_f32 v[44:45], v[106:107], v[24:25], v[12:13]
	v_pk_fma_f32 v[60:61], v[110:111], v[30:31], v[10:11]
	v_cvt_pk_bf16_f32 v44, v44, v45
	v_cvt_pk_bf16_f32 v45, v46, v47
	v_pk_fma_f32 v[46:47], v[108:109], v[28:29], v[8:9]
	v_cvt_pk_bf16_f32 v40, v24, v25
	v_cvt_pk_bf16_f32 v46, v46, v47
	v_cvt_pk_bf16_f32 v47, v60, v61
	v_lshlrev_b64 v[60:61], 11, v[56:57]
	v_lshl_add_u64 v[62:63], s[30:31], 0, v[60:61]
	v_cvt_pk_bf16_f32 v41, v26, v27
	v_cvt_pk_bf16_f32 v42, v28, v29
	v_cvt_pk_bf16_f32 v43, v30, v31
	v_lshl_add_u64 v[62:63], v[62:63], 0, v[74:75]
	global_store_dwordx4 v[62:63], v[40:43], off sc1
	s_mov_b64 s[50:51], 0
	s_nop 0
	v_lshl_add_u64 v[40:41], s[42:43], 0, v[60:61]
	v_lshl_add_u64 v[40:41], v[40:41], 0, v[74:75]
	global_store_dwordx4 v[40:41], v[44:47], off sc1

.LBB0_762:
	s_nop 0
	v_or_b32_e32 v24, 48, v114
	v_lshl_add_u32 v25, v24, 3, 0
	v_add_u32_e32 v25, 0x24000, v25
	ds_read_b64 v[42:43], v25
	v_add_u32_e32 v40, s63, v24
	s_mov_b64 s[50:51], -1
	s_and_b64 vcc, exec, s[40:41]
	v_ashrrev_i32_e32 v41, 31, v40
	s_waitcnt lgkmcnt(0)
	v_sub_f32_e32 v25, v97, v42
	v_sub_f32_e32 v24, v96, v42
	v_sub_f32_e32 v27, v95, v42
	v_sub_f32_e32 v26, v94, v42
	v_pk_mul_f32 v[26:27], v[26:27], v[42:43] op_sel:[0,1]
	v_pk_mul_f32 v[24:25], v[24:25], v[42:43] op_sel:[0,1]
	v_pk_fma_f32 v[16:17], v[16:17], v[26:27], v[20:21]
	v_pk_fma_f32 v[18:19], v[18:19], v[24:25], v[22:23]
	v_sub_f32_e32 v21, v93, v42
	v_sub_f32_e32 v20, v92, v42
	v_sub_f32_e32 v23, v91, v42
	v_sub_f32_e32 v22, v90, v42
	v_pk_mul_f32 v[22:23], v[42:43], v[22:23] op_sel:[1,0]
	v_pk_mul_f32 v[20:21], v[42:43], v[20:21] op_sel:[1,0]
	v_pk_fma_f32 v[0:1], v[0:1], v[22:23], v[4:5]
	v_pk_fma_f32 v[2:3], v[2:3], v[20:21], v[6:7]
	s_cbranch_vccnz .LBB0_764
	v_pk_fma_f32 v[14:15], v[112:113], v[18:19], v[14:15]
	v_pk_fma_f32 v[12:13], v[106:107], v[16:17], v[12:13]
	v_pk_fma_f32 v[8:9], v[108:109], v[0:1], v[8:9]
	v_cvt_pk_bf16_f32 v12, v12, v13
	v_cvt_pk_bf16_f32 v13, v14, v15
	v_pk_fma_f32 v[10:11], v[110:111], v[2:3], v[10:11]
	v_cvt_pk_bf16_f32 v14, v8, v9
	v_lshlrev_b64 v[8:9], 11, v[40:41]
	v_cvt_pk_bf16_f32 v15, v10, v11
	v_lshl_add_u64 v[10:11], s[30:31], 0, v[8:9]
	v_cvt_pk_bf16_f32 v4, v16, v17
	v_cvt_pk_bf16_f32 v5, v18, v19
	v_cvt_pk_bf16_f32 v6, v0, v1
	v_cvt_pk_bf16_f32 v7, v2, v3
	v_lshl_add_u64 v[10:11], v[10:11], 0, v[74:75]
	global_store_dwordx4 v[10:11], v[4:7], off sc1
	s_mov_b64 s[50:51], 0
	s_nop 0
	v_lshl_add_u64 v[4:5], s[42:43], 0, v[8:9]
	v_lshl_add_u64 v[4:5], v[4:5], 0, v[74:75]
	global_store_dwordx4 v[4:5], v[12:15], off sc1

.LBB0_769:
	v_mov_b32_e32 v28, v101
	v_mov_b32_e32 v29, v101
	v_sub_f32_e32 v25, v71, v100
	v_sub_f32_e32 v24, v70, v100
	v_sub_f32_e32 v27, v69, v100
	v_sub_f32_e32 v26, v68, v100
	v_mov_b32_e32 v68, v101
	v_mov_b32_e32 v69, v101
	v_pk_mul_f32 v[30:31], v[26:27], v[28:29]
	v_pk_mul_f32 v[24:25], v[24:25], v[68:69]
	v_sub_f32_e32 v65, v65, v100
	s_waitcnt vmcnt(0)
	v_pk_fma_f32 v[26:27], v[24:25], v[18:19], v[22:23]
	v_pk_fma_f32 v[24:25], v[30:31], v[16:17], v[20:21]
	v_sub_f32_e32 v31, v67, v100
	v_sub_f32_e32 v30, v66, v100
	v_sub_f32_e32 v64, v64, v100
	v_pk_mul_f32 v[28:29], v[28:29], v[64:65]
	v_pk_mul_f32 v[30:31], v[68:69], v[30:31]
	v_pk_fma_f32 v[28:29], v[28:29], v[0:1], v[4:5]
	v_pk_fma_f32 v[30:31], v[30:31], v[2:3], v[6:7]
	s_and_b64 vcc, exec, s[40:41]
	s_mov_b64 s[44:45], -1
	s_cbranch_vccnz .LBB0_771
	v_pk_fma_f32 v[70:71], v[26:27], v[62:63], v[14:15]
	v_pk_fma_f32 v[68:69], v[24:25], v[44:45], v[12:13]
	v_pk_fma_f32 v[80:81], v[30:31], v[60:61], v[10:11]
	v_cvt_pk_bf16_f32 v68, v68, v69
	v_cvt_pk_bf16_f32 v69, v70, v71
	v_pk_fma_f32 v[70:71], v[28:29], v[46:47], v[8:9]
	v_cvt_pk_bf16_f32 v64, v24, v25
	v_cvt_pk_bf16_f32 v70, v70, v71
	v_cvt_pk_bf16_f32 v71, v80, v81
	v_lshlrev_b64 v[80:81], 11, v[98:99]
	v_lshl_add_u64 v[90:91], s[30:31], 0, v[80:81]
	v_cvt_pk_bf16_f32 v65, v26, v27
	v_cvt_pk_bf16_f32 v66, v28, v29
	v_cvt_pk_bf16_f32 v67, v30, v31
	v_lshl_add_u64 v[90:91], v[90:91], 0, v[74:75]
	global_store_dwordx4 v[90:91], v[64:67], off offset:64 sc1
	s_mov_b64 s[44:45], 0
	s_nop 0
	v_lshl_add_u64 v[64:65], s[42:43], 0, v[80:81]
	v_lshl_add_u64 v[64:65], v[64:65], 0, v[74:75]
	global_store_dwordx4 v[64:65], v[68:71], off offset:64 sc1

.LBB0_773:
	s_nop 1
	v_mov_b32_e32 v28, v79
	v_mov_b32_e32 v29, v79
	v_sub_f32_e32 v25, v55, v78
	v_sub_f32_e32 v24, v54, v78
	v_sub_f32_e32 v27, v53, v78
	v_sub_f32_e32 v26, v52, v78
	v_mov_b32_e32 v52, v79
	v_mov_b32_e32 v53, v79
	v_pk_mul_f32 v[30:31], v[26:27], v[28:29]
	v_pk_mul_f32 v[24:25], v[24:25], v[52:53]
	v_sub_f32_e32 v49, v49, v78
	v_pk_fma_f32 v[26:27], v[24:25], v[18:19], v[22:23]
	v_pk_fma_f32 v[24:25], v[30:31], v[16:17], v[20:21]
	v_sub_f32_e32 v31, v51, v78
	v_sub_f32_e32 v30, v50, v78
	v_sub_f32_e32 v48, v48, v78
	v_pk_mul_f32 v[28:29], v[28:29], v[48:49]
	v_pk_mul_f32 v[30:31], v[52:53], v[30:31]
	v_pk_fma_f32 v[28:29], v[28:29], v[0:1], v[4:5]
	v_pk_fma_f32 v[30:31], v[30:31], v[2:3], v[6:7]
	s_and_b64 vcc, exec, s[40:41]
	s_mov_b64 s[44:45], -1
	s_cbranch_vccnz .LBB0_775
	v_pk_fma_f32 v[54:55], v[26:27], v[62:63], v[14:15]
	v_pk_fma_f32 v[52:53], v[24:25], v[44:45], v[12:13]
	v_pk_fma_f32 v[64:65], v[30:31], v[60:61], v[10:11]
	v_cvt_pk_bf16_f32 v52, v52, v53
	v_cvt_pk_bf16_f32 v53, v54, v55
	v_pk_fma_f32 v[54:55], v[28:29], v[46:47], v[8:9]
	v_cvt_pk_bf16_f32 v48, v24, v25
	v_cvt_pk_bf16_f32 v54, v54, v55
	v_cvt_pk_bf16_f32 v55, v64, v65
	v_lshlrev_b64 v[64:65], 11, v[76:77]
	v_lshl_add_u64 v[66:67], s[30:31], 0, v[64:65]
	v_cvt_pk_bf16_f32 v49, v26, v27
	v_cvt_pk_bf16_f32 v50, v28, v29
	v_cvt_pk_bf16_f32 v51, v30, v31
	v_lshl_add_u64 v[66:67], v[66:67], 0, v[74:75]
	global_store_dwordx4 v[66:67], v[48:51], off offset:64 sc1
	s_mov_b64 s[44:45], 0
	s_nop 0
	v_lshl_add_u64 v[48:49], s[42:43], 0, v[64:65]
	v_lshl_add_u64 v[48:49], v[48:49], 0, v[74:75]
	global_store_dwordx4 v[48:49], v[52:55], off offset:64 sc1

.LBB0_777:
	s_nop 1
	v_mov_b32_e32 v28, v59
	v_mov_b32_e32 v29, v59
	v_sub_f32_e32 v25, v39, v58
	v_sub_f32_e32 v24, v38, v58
	v_sub_f32_e32 v27, v37, v58
	v_sub_f32_e32 v26, v36, v58
	v_mov_b32_e32 v36, v59
	v_mov_b32_e32 v37, v59
	v_pk_mul_f32 v[30:31], v[26:27], v[28:29]
	v_pk_mul_f32 v[24:25], v[24:25], v[36:37]
	v_sub_f32_e32 v33, v33, v58
	v_pk_fma_f32 v[26:27], v[24:25], v[18:19], v[22:23]
	v_pk_fma_f32 v[24:25], v[30:31], v[16:17], v[20:21]
	v_sub_f32_e32 v31, v35, v58
	v_sub_f32_e32 v30, v34, v58
	v_sub_f32_e32 v32, v32, v58
	v_pk_mul_f32 v[28:29], v[28:29], v[32:33]
	v_pk_mul_f32 v[30:31], v[36:37], v[30:31]
	v_pk_fma_f32 v[28:29], v[28:29], v[0:1], v[4:5]
	v_pk_fma_f32 v[30:31], v[30:31], v[2:3], v[6:7]
	s_and_b64 vcc, exec, s[40:41]
	s_mov_b64 s[44:45], -1
	s_cbranch_vccnz .LBB0_779
	v_pk_fma_f32 v[38:39], v[26:27], v[62:63], v[14:15]
	v_pk_fma_f32 v[36:37], v[24:25], v[44:45], v[12:13]
	v_pk_fma_f32 v[48:49], v[30:31], v[60:61], v[10:11]
	v_cvt_pk_bf16_f32 v36, v36, v37
	v_cvt_pk_bf16_f32 v37, v38, v39
	v_pk_fma_f32 v[38:39], v[28:29], v[46:47], v[8:9]
	v_cvt_pk_bf16_f32 v32, v24, v25
	v_cvt_pk_bf16_f32 v38, v38, v39
	v_cvt_pk_bf16_f32 v39, v48, v49
	v_lshlrev_b64 v[48:49], 11, v[56:57]
	v_lshl_add_u64 v[50:51], s[30:31], 0, v[48:49]
	v_cvt_pk_bf16_f32 v33, v26, v27
	v_cvt_pk_bf16_f32 v34, v28, v29
	v_cvt_pk_bf16_f32 v35, v30, v31
	v_lshl_add_u64 v[50:51], v[50:51], 0, v[74:75]
	global_store_dwordx4 v[50:51], v[32:35], off offset:64 sc1
	s_mov_b64 s[44:45], 0
	s_nop 0
	v_lshl_add_u64 v[32:33], s[42:43], 0, v[48:49]
	v_lshl_add_u64 v[32:33], v[32:33], 0, v[74:75]
	global_store_dwordx4 v[32:33], v[36:39], off offset:64 sc1

.LBB0_781:
	s_nop 0
	v_mov_b32_e32 v24, v43
	v_mov_b32_e32 v25, v43
	v_sub_f32_e32 v27, v85, v42
	v_sub_f32_e32 v26, v84, v42
	v_sub_f32_e32 v29, v83, v42
	v_sub_f32_e32 v28, v82, v42
	v_mov_b32_e32 v30, v43
	v_mov_b32_e32 v31, v43
	v_pk_mul_f32 v[28:29], v[28:29], v[24:25]
	v_pk_mul_f32 v[26:27], v[26:27], v[30:31]
	v_pk_fma_f32 v[16:17], v[28:29], v[16:17], v[20:21]
	v_pk_fma_f32 v[18:19], v[26:27], v[18:19], v[22:23]
	v_sub_f32_e32 v21, v89, v42
	v_sub_f32_e32 v20, v88, v42
	v_sub_f32_e32 v23, v87, v42
	v_sub_f32_e32 v22, v86, v42
	v_pk_mul_f32 v[22:23], v[24:25], v[22:23]
	v_pk_mul_f32 v[20:21], v[30:31], v[20:21]
	v_pk_fma_f32 v[0:1], v[22:23], v[0:1], v[4:5]
	v_pk_fma_f32 v[2:3], v[20:21], v[2:3], v[6:7]
	s_and_b64 vcc, exec, s[40:41]
	s_mov_b64 s[40:41], -1
	s_cbranch_vccnz .LBB0_783
	v_pk_fma_f32 v[14:15], v[18:19], v[62:63], v[14:15]
	v_pk_fma_f32 v[12:13], v[16:17], v[44:45], v[12:13]
	v_pk_fma_f32 v[8:9], v[0:1], v[46:47], v[8:9]
	v_cvt_pk_bf16_f32 v12, v12, v13
	v_cvt_pk_bf16_f32 v13, v14, v15
	v_pk_fma_f32 v[10:11], v[2:3], v[60:61], v[10:11]
	v_cvt_pk_bf16_f32 v14, v8, v9
	v_lshlrev_b64 v[8:9], 11, v[40:41]
	v_cvt_pk_bf16_f32 v15, v10, v11
	v_lshl_add_u64 v[10:11], s[30:31], 0, v[8:9]
	v_cvt_pk_bf16_f32 v4, v16, v17
	v_cvt_pk_bf16_f32 v5, v18, v19
	v_cvt_pk_bf16_f32 v6, v0, v1
	v_cvt_pk_bf16_f32 v7, v2, v3
	v_lshl_add_u64 v[10:11], v[10:11], 0, v[74:75]
	global_store_dwordx4 v[10:11], v[4:7], off offset:64 sc1
	s_mov_b64 s[40:41], 0
	s_nop 0
	v_lshl_add_u64 v[4:5], s[42:43], 0, v[8:9]
	v_lshl_add_u64 v[4:5], v[4:5], 0, v[74:75]
	global_store_dwordx4 v[4:5], v[12:15], off offset:64 sc1

.LBB0_871:
	s_lshl_b32 s24, s30, 8
	v_ashrrev_i32_e32 v33, 31, v40
	v_mad_u64_u32 v[40:41], s[30:31], v40, s44, 0
	v_mov_b32_e32 v42, v41
	v_mad_u64_u32 v[42:43], s[30:31], v33, s44, v[42:43]
	v_mov_b32_e32 v41, v42
	v_lshl_add_u64 v[40:41], v[40:41], 1, s[0:1]
	s_ashr_i32 s25, s24, 31
	v_lshl_add_u64 v[44:45], s[24:25], 1, v[40:41]
	ds_read2_b32 v[40:41], v39 offset1:65
	ds_read2_b32 v[42:43], v39 offset0:130 offset1:195
	v_add_u32_e32 v33, 0x400, v39
	ds_read2_b32 v[46:47], v33 offset0:134 offset1:199
	v_lshl_add_u64 v[44:45], v[44:45], 0, v[144:145]
	s_waitcnt lgkmcnt(2)
	v_cvt_pk_bf16_f32 v40, v40, v41
	s_waitcnt lgkmcnt(1)
	v_cvt_pk_bf16_f32 v41, v42, v43
	ds_read2_b32 v[42:43], v33 offset0:4 offset1:69
	v_add_u32_e32 v33, 0x4000, v39
	s_and_b64 vcc, exec, s[4:5]
	s_mov_b32 s41, s46
	s_mov_b64 s[0:1], s[28:29]
	s_waitcnt lgkmcnt(0)
	v_cvt_pk_bf16_f32 v42, v42, v43
	v_cvt_pk_bf16_f32 v43, v46, v47
	global_store_dwordx4 v[44:45], v[40:43], off sc1
	ds_read2_b32 v[40:41], v33 offset0:64 offset1:129
	v_add_u32_e32 v33, 0x4200, v39
	ds_read2_b32 v[42:43], v33 offset0:66 offset1:131
	v_add_u32_e32 v33, 0x4400, v39
	s_mov_b32 s44, s50
	s_waitcnt lgkmcnt(1)
	v_cvt_pk_bf16_f32 v40, v40, v41
	s_mov_b32 s43, s47
	s_waitcnt lgkmcnt(0)
	v_cvt_pk_bf16_f32 v41, v42, v43
	ds_read2_b32 v[42:43], v33 offset0:68 offset1:133
	v_add_u32_e32 v33, 0x4600, v39
	ds_read2_b32 v[46:47], v33 offset0:70 offset1:135
	v_add_u32_e32 v33, 0x8000, v39
	s_mov_b32 s42, s51
	s_waitcnt lgkmcnt(1)
	v_cvt_pk_bf16_f32 v42, v42, v43
	s_mov_b32 s33, s45
	s_waitcnt lgkmcnt(0)
	v_cvt_pk_bf16_f32 v43, v46, v47
	global_store_dwordx4 v[44:45], v[40:43], off offset:128 sc1
	ds_read2_b32 v[40:41], v33 offset0:128 offset1:193
	v_add_u32_e32 v33, 0x8400, v39
	ds_read2_b32 v[42:43], v33 offset0:2 offset1:67
	s_waitcnt lgkmcnt(1)
	v_cvt_pk_bf16_f32 v40, v40, v41
	s_waitcnt lgkmcnt(0)
	v_cvt_pk_bf16_f32 v41, v42, v43
	ds_read2_b32 v[42:43], v33 offset0:132 offset1:197
	v_add_u32_e32 v33, 0x8800, v39
	ds_read2_b32 v[46:47], v33 offset0:6 offset1:71
	v_add_u32_e32 v33, 0xc200, v39
	s_waitcnt lgkmcnt(1)
	v_cvt_pk_bf16_f32 v42, v42, v43
	s_waitcnt lgkmcnt(0)
	v_cvt_pk_bf16_f32 v43, v46, v47
	global_store_dwordx4 v[44:45], v[40:43], off offset:256 sc1
	ds_read2_b32 v[40:41], v33 offset0:64 offset1:129
	v_add_u32_e32 v33, 0xc400, v39
	ds_read2_b32 v[42:43], v33 offset0:66 offset1:131
	v_add_u32_e32 v33, 0xc600, v39
	s_waitcnt lgkmcnt(1)
	v_cvt_pk_bf16_f32 v40, v40, v41
	s_waitcnt lgkmcnt(0)
	v_cvt_pk_bf16_f32 v41, v42, v43
	ds_read2_b32 v[42:43], v33 offset0:68 offset1:133
	v_add_u32_e32 v33, 0xc800, v39
	ds_read2_b32 v[46:47], v33 offset0:70 offset1:135
	s_waitcnt lgkmcnt(1)
	v_cvt_pk_bf16_f32 v42, v42, v43
	s_waitcnt lgkmcnt(0)
	v_cvt_pk_bf16_f32 v43, v46, v47
	global_store_dwordx4 v[44:45], v[40:43], off offset:384 sc1
	s_barrier
	s_cbranch_vccnz .LBB0_955

.LBB0_1515:
	s_or_b64 exec, exec, s[4:5]
	v_cvt_f32_u32_e32 v4, v2
	s_waitcnt vmcnt(0)
	v_readfirstlane_b32 s4, v3
	v_sub_u32_e32 v3, 0, v2
	v_rcp_iflag_f32_e32 v4, v4
	v_add_u32_e32 v5, s4, v1
	v_mul_f32_e32 v4, 0x4f7ffffe, v4
	v_cvt_u32_f32_e32 v4, v4
	v_mul_lo_u32 v1, v3, v4
	v_mul_hi_u32 v1, v4, v1
	v_add_u32_e32 v1, v4, v1
	v_mul_hi_u32 v1, v5, v1
	v_mul_lo_u32 v3, v1, v2
	v_sub_u32_e32 v3, v5, v3
	v_add_u32_e32 v4, 1, v1
	v_cmp_ge_u32_e32 vcc, v3, v2
	s_nop 1
	v_cndmask_b32_e32 v1, v1, v4, vcc
	v_sub_u32_e32 v4, v3, v2
	v_cndmask_b32_e32 v3, v3, v4, vcc
	v_add_u32_e32 v4, 1, v1
	v_cmp_ge_u32_e32 vcc, v3, v2
	v_add_u32_e32 v3, 1, v5
	s_nop 0
	v_cndmask_b32_e32 v1, v1, v4, vcc
	v_mul_lo_u32 v4, v2, v1
	v_add_u32_e32 v2, v4, v2
	v_cmp_ne_u32_e32 vcc, v3, v2
	s_waitcnt lgkmcnt(0)
	v_add_u32_e32 v6, 1, v1
	v_mul_lo_u32 v6, v6, v0
	s_cbranch_vccnz .Lnb_poll
	s_mov_b32 s28, 0x1183180
	s_lshr_b32 s28, s28, s54
	s_bitcmp1_b32 s28, 0
	s_cbranch_scc1 .Lnb_nowb
	buffer_wbl2 sc1
	s_waitcnt vmcnt(0)
